# mLSTM: barrier 3 moved up behind [C]'s LDS reads; Cs bf16 writes overlap the MFMA chain and epilogue
# baseline (speedup 1.0000x reference)
; #define LAS __attribute__((address_space(3)))
; __device__ __forceinline__ float bf2f(unsigned b) { return __uint_as_float(b << 16); }
; __device__ __forceinline__ unsigned pk2(float lo, float hi) { unsigned r; asm("v_cvt_pk_bf16_f32 %0, %1, %2" : "=v"(r) : "v"(lo), "v"(hi)); return r; }
; #define LDS_BARRIER() do { asm volatile("s_waitcnt lgkmcnt(0)" ::: "memory"); __builtin_amdgcn_s_barrier(); asm volatile("" ::: "memory"); } while (0)
; __device__ __forceinline__ void mlstm_item(const Args& a, LAS unsigned char* L, bool sample, int b, int hh, int sl, bool dry = false) {
;     ...
;     for (int idx = tid; idx < nchunks * 32; idx += 512) { const int c = idx >> 5; const float m0c = GM0[c], cm = GFM[idx], F = GEN[idx], aa = GAA[idx], mm = fmaxf(m0c, cm);
;         GFM[idx] = -mm; GEN[idx] = __expf(-(F + mm)); GWL[idx] = __expf(aa + GX[c]); }
;     LDS_BARRIER();
;     for (int c = 0; c < nchunks; ++c) {
; #pragma unroll
;         for (int i = 0; i < 2; ++i) { *(LAS u32x4*)(L + L_QS + (prow + 16 * i) * 528 + pcc * 16) = qreg[i]; *(LAS u32x4*)(L + L_KS + (prow + 16 * i) * 528 + pcc * 16) = kreg[i]; }
;         if (tid < 256) {
;             const float wL0 = GWL[c * 32 + 2 * sp], wL1 = GWL[c * 32 + 2 * sp + 1];
;             const unsigned r0w[2] = {vreg0.x, vreg0.y}, r1w[2] = {vreg1.x, vreg1.y};
; #pragma unroll
;             for (int i = 0; i < 4; ++i) { const unsigned e0 = (i & 1) ? (r0w[i >> 1] >> 16) : (r0w[i >> 1] & 0xffffu), e1 = (i & 1) ? (r1w[i >> 1] >> 16) : (r1w[i >> 1] & 0xffffu);
;                 *(LAS unsigned*)(L + L_VT + (vq * 4 + i) * 80 + sp * 4) = e0 | (e1 << 16);
;                 *(LAS unsigned*)(L + L_VTW + (vq * 4 + i) * 80 + sp * 4) = pk2(bf2f(e0) * wL0, bf2f(e1) * wL1); }
;             if (tid < 16) *(LAS unsigned*)(L + L_VTW + 64 * 80 + sp * 4) = pk2(wL0, wL1);
;         }
;         if (c + 1 < nchunks) PREFETCH(c + 1);
;         LDS_BARRIER();
;         const float dL = GDL[c], m0c = GM0[c];
;         if (wave < 4) {
;             const int st = wave >> 1, tt = wave & 1, t = tt * 16 + lr;
.LBB0_659:
	s_or_b64 exec, exec, s[4:5]
	s_lshr_b32 s4, s92, 3
	s_and_b32 s59, s4, 3
	s_lshl_b32 s97, s94, 6
	s_cmp_gt_i32 s55, 3
	s_cselect_b64 s[68:69], -1, 0
	s_add_i32 s4, s55, -4
	s_lshr_b32 s6, s4, 1
	v_and_b32_e32 v99, 48, v83
	v_bfe_u32 v222, v83, 5, 1
	v_lshlrev_b32_e32 v222, 4, v222
	v_bfe_u32 v223, v83, 4, 1
	v_lshl_or_b32 v222, v223, 8, v222
	v_bfe_u32 v223, v83, 5, 1
	v_mul_u32_u24_e32 v223, 0xf0, v223
	v_lshrrev_b32_e32 v226, 1, v83
	v_and_b32_e32 v226, 0xffffffe0, v226
	v_sub_u32_e32 v223, v223, v226
	v_bfe_u32 v224, v83, 2, 3
	v_lshlrev_b32_e32 v224, 5, v224
	v_bfe_u32 v227, v83, 1, 1
	v_lshl_or_b32 v224, v227, 4, v224
	v_and_b32_e32 v228, 1, v83
	v_lshl_or_b32 v224, v228, 8, v224
	v_lshlrev_b32_e32 v225, 8, v227
	v_lshl_or_b32 v225, v228, 3, v225
	v_add_u32_e32 v225, v225, v226
	s_lshl_b32 s4, s55, 4
	v_lshl_add_u32 v103, s6, 7, v222
	s_lshl_b32 s6, s6, 5
	v_lshlrev_b32_e32 v66, 2, v84
	s_and_b32 s17, s4, 16
	s_add_i32 s6, s6, 64
	s_ashr_i32 s70, s12, 7
	s_bfe_u32 s71, s12, 0x10006
	v_lshl_add_u32 v21, v24, 4, 0
	v_add_u32_e32 v106, 0, v66
	v_or_b32_e32 v88, s17, v84
	v_mul_u32_u24_e32 v24, 0x20c, v84
	s_mov_b32 s4, 0xc000
	s_cmp_lg_u32 s70, 1
	v_add3_u32 v105, v106, v24, s4
	v_or_b32_e32 v24, s6, v88
	s_cselect_b64 s[6:7], -1, 0
	s_bitcmp1_b32 s12, 6
	s_cselect_b64 s[8:9], -1, 0
	s_or_b64 s[64:65], s[6:7], s[8:9]
	s_lshl_b32 s6, s70, 4
	v_lshlrev_b32_e32 v102, 2, v24
	v_or_b32_e32 v24, s6, v84
	v_mul_lo_u32 v24, v24, s83
	v_lshlrev_b32_e32 v68, 2, v23
	v_add_u32_e32 v101, 0, v24
	v_or_b32_e32 v98, s6, v68
	s_and_b32 s6, s12, 0xffffff80
	v_lshrrev_b32_e32 v24, 2, v84
	s_add_i32 s86, s35, s6
	v_or_b32_e32 v24, v26, v24
	s_ashr_i32 s6, s12, 3
	s_lshl_b32 s16, s58, 9
	v_mad_u32_u24 v28, v24, s83, 0
	v_lshlrev_b32_e32 v24, 3, v83
	s_and_b32 s56, s6, -16
	s_add_i32 s42, s42, s16
	v_and_or_b32 v29, v24, 24, s13
	v_or_b32_e32 v24, s56, v84
	s_and_b32 s16, s42, 0xfffff800
	v_mul_lo_u32 v26, v24, s82
	s_or_b32 s17, s16, s17
	v_add_u32_e32 v70, 0, v26
	s_movk_i32 s6, 0x1c0
	v_or_b32_e32 v109, s17, v84
	s_lshl_b32 s17, s70, 6
	v_cmp_gt_u32_e64 s[4:5], 16, v27
	v_lshl_or_b32 v96, s71, 4, v84
	v_mad_u64_u32 v[26:27], s[6:7], v24, s6, v[70:71]
	v_or_b32_e32 v24, 2, v98
	s_add_i32 s17, s17, 0x18500
	v_cmp_gt_i32_e64 s[10:11], v24, v96
	v_or_b32_e32 v24, 3, v98
	v_lshl_or_b32 v111, v23, 4, s17
	v_mul_hi_u32_u24_e32 v23, 0x7000, v84
	s_mul_hi_i32 s42, s16, 0x3800
	v_mul_lo_u32 v108, v25, s87
	v_cmp_gt_i32_e64 s[6:7], v24, v96
	v_mul_u32_u24_e32 v24, 0x7000, v84
	s_mul_i32 s58, s16, 0x3800
	v_or_b32_e32 v25, s42, v23
	s_lshl_b32 s42, s92, 4
	v_or_b32_e32 v23, s58, v24
	s_and_b32 s42, s42, 0x600
	s_mul_i32 s100, s16, 0x3800
	s_mul_hi_u32 s101, s16, 0x3800
	s_add_u32 s100, s100, s28
	s_addc_u32 s101, s101, s29
	s_add_u32 s100, s100, s42
	s_addc_u32 s101, s101, 0
	s_add_u32 s100, s100, 0x2000
	s_addc_u32 s101, s101, 0
	v_or_b32_e32 v23, s42, v23
	s_ashr_i32 s17, s16, 31
	v_lshl_or_b32 v24, s59, 7, v23
	v_mul_lo_u32 v27, v16, s83
	v_lshl_add_u64 v[18:19], v[18:19], 1, v[24:25]
	v_lshl_add_u64 v[16:17], v[16:17], 0, s[16:17]
	s_waitcnt lgkmcnt(0)
	s_barrier
; #define LAS __attribute__((address_space(3)))
; #define WRITE_CS() do { _Pragma("unroll") for (int kti = 0; kti < 2; ++kti) _Pragma("unroll") for (int vt = 0; vt < 5; ++vt) \
;         *(LAS u32x2*)(L + L_CS + (vt * 16 + lr) * 528 + ((2 * wave + kti) * 16 + g * 4) * 2) = (u32x2){pk2(Cacc[kti][vt][0], Cacc[kti][vt][1]), pk2(Cacc[kti][vt][2], Cacc[kti][vt][3])}; } while (0)
; __device__ __forceinline__ void mlstm_item(const Args& a, LAS unsigned char* L, bool sample, int b, int hh, int sl, bool dry = false) {
;     ...
;     { const int row = 64 + (tid >> 5), s = tid & 31;
;       *(LAS bf16_t*)(L + L_VT + row * 80 + s * 2) = (row == 64) ? (bf16_t)0x3F80 : (bf16_t)0;
;       *(LAS bf16_t*)(L + L_VTW + row * 80 + s * 2) = (bf16_t)0; }
;     f32x4 Cacc[2][5];
; #pragma unroll
;     for (int kti = 0; kti < 2; ++kti)
; #pragma unroll
;         for (int vt = 0; vt < 5; ++vt) Cacc[kti][vt] = (f32x4){0.f, 0.f, 0.f, 0.f};
;     float m_init = 0.f;
;     if (sample) {
;         const float* sC = a.in[5] + (size_t)(b * 4 + hh) * 65536; const float* sn = a.in[6] + (size_t)(b * 4 + hh) * 256;
; #pragma unroll
;         for (int kti = 0; kti < 2; ++kti)
; #pragma unroll
;             for (int j = 0; j < 4; ++j) { const int k = (2 * wave + kti) * 16 + g * 4 + j;
; #pragma unroll
;                 for (int vt = 0; vt < 4; ++vt) Cacc[kti][vt][j] = sC[(size_t)k * 256 + sl * 64 + vt * 16 + lr];
;                 Cacc[kti][4][j] = (lr == 0) ? sn[k] : 0.f; }
;         m_init = a.in[7][b * 4 + hh];
;     }
;     ...
;     WRITE_CS();
;     u32x4 qreg[2], kreg[2]; u32x2 vreg0 = (u32x2){0u, 0u}, vreg1 = vreg0;
;     const int prow = tid >> 5, pcc = tid & 31;
;     const int sp = tid & 15, vq = tid >> 4;
;     ...
;     PREFETCH(0);
	v_mad_u32_u24 v104, v88, s83, 0
	v_lshl_add_u64 v[72:73], s[28:29], 0, v[18:19]
	v_mad_u64_u32 v[18:19], s[16:17], v16, s84, 0
	v_mul_u32_u24_e32 v20, 0x210, v84
	v_lshlrev_b32_e32 v107, 3, v84
	v_mad_u32_u24 v100, v96, s83, 0
	v_add_u32_e32 v30, 0, v99
	v_mad_i32_i24 v31, v88, s33, v104
	v_mul_u32_u24_e32 v32, 0x50, v84
	v_mad_i32_i24 v17, v17, s84, v19
	v_or3_b32 v16, v18, s42, v60
	v_mov_b32_e32 v36, 0
	v_cmp_gt_i32_e64 s[14:15], 16, v83
	v_mad_i32_i24 v93, v96, s33, v100
	v_lshlrev_b32_e32 v94, 1, v98
	v_lshlrev_b32_e32 v92, 2, v96
	v_lshl_add_u32 v89, v88, 2, s35
	s_ashr_i32 s57, s56, 31
	v_cmp_gt_i32_e64 s[12:13], v98, v96
	v_cmp_lt_i32_e64 s[8:9], v98, v96
	v_lshl_or_b32 v110, s71, 6, v66
	v_lshl_add_u64 v[74:75], s[28:29], 0, v[16:17]
	s_mov_b32 s16, 0
	s_mov_b64 s[70:71], 0
	s_lshl_b32 s58, s97, 1
	v_lshlrev_b32_e32 v60, 1, v68
	v_add_u32_e32 v112, v224, v27
	v_add_u32_e32 v97, v28, v225
	v_add_u32_e32 v95, v30, v32
	v_add_u32_e32 v91, v31, v99
	v_add_u32_e32 v90, v26, v222
	v_add_u32_e32 v113, v22, v20
	v_add_u32_e32 v113, v113, v223
	v_add_u32_e32 v86, v86, v223
	v_add_u32_e32 v85, v85, v223
	v_add_u32_e32 v67, v67, v223
	v_mov_b32_e32 v114, v107
	v_mov_b32_e32 v37, v36
	v_mov_b32_e32 v38, v36
	v_mov_b32_e32 v39, v36
	v_mov_b32_e32 v52, v36
	v_mov_b32_e32 v53, v36
	v_mov_b32_e32 v54, v36
	v_mov_b32_e32 v55, v36
	v_mov_b32_e32 v48, v36
	v_mov_b32_e32 v49, v36
	v_mov_b32_e32 v50, v36
	v_mov_b32_e32 v51, v36
	v_mov_b32_e32 v44, v36
	v_mov_b32_e32 v45, v36
	v_mov_b32_e32 v46, v36
	v_mov_b32_e32 v47, v36
	v_mov_b32_e32 v40, v36
	v_mov_b32_e32 v41, v36
	v_mov_b32_e32 v42, v36
	v_mov_b32_e32 v43, v36
	v_mov_b32_e32 v32, v36
	v_mov_b32_e32 v33, v36
	v_mov_b32_e32 v34, v36
	v_mov_b32_e32 v35, v36
	v_mov_b32_e32 v28, v36
	v_mov_b32_e32 v29, v36
	v_mov_b32_e32 v30, v36
	v_mov_b32_e32 v31, v36
	v_mov_b32_e32 v24, v36
	v_mov_b32_e32 v25, v36
	v_mov_b32_e32 v26, v36
	v_mov_b32_e32 v27, v36
	v_mov_b32_e32 v20, v36
	v_mov_b32_e32 v21, v36
	v_mov_b32_e32 v22, v36
	v_mov_b32_e32 v23, v36
	v_mov_b32_e32 v16, v36
	v_mov_b32_e32 v17, v36
	v_mov_b32_e32 v18, v36
	v_mov_b32_e32 v19, v36
	v_add_u32_e32 v239, v104, v222
	v_add_u32_e32 v248, 0xc000, v113
	v_add_u32_e32 v249, 0xe000, v113
	v_add_u32_e32 v250, 0xe000, v86
	v_mov_b32_e32 v234, v83
	v_mul_u32_u24_e32 v235, 0x7c2, v234
	v_lshrrev_b32_e32 v235, 16, v235
	v_mul_u32_u24_e32 v236, 33, v235
	v_sub_u32_e32 v236, v234, v236
	v_and_b32_e32 v237, 15, v236
	v_lshrrev_b32_e32 v238, 1, v237
	v_lshlrev_b32_e32 v238, 6, v238
	v_and_b32_e32 v237, 1, v237
	v_lshl_or_b32 v238, v237, 5, v238
	v_lshrrev_b32_e32 v237, 4, v236
	v_lshl_or_b32 v238, v237, 4, v238
	v_lshrrev_b32_e32 v237, 5, v235
	v_lshl_or_b32 v238, v237, 11, v238
	v_and_b32_e32 v237, 31, v235
	v_mul_u32_u24_e32 v237, 0x3800, v237
	v_add_u32_e32 v229, v237, v238
	v_add_u32_e32 v234, 512, v83
	v_mul_u32_u24_e32 v235, 0x7c2, v234
	v_lshrrev_b32_e32 v235, 16, v235
	v_mul_u32_u24_e32 v236, 33, v235
	v_sub_u32_e32 v236, v234, v236
	v_and_b32_e32 v237, 15, v236
	v_lshrrev_b32_e32 v238, 1, v237
	v_lshlrev_b32_e32 v238, 6, v238
	v_and_b32_e32 v237, 1, v237
	v_lshl_or_b32 v238, v237, 5, v238
	v_lshrrev_b32_e32 v237, 4, v236
	v_lshl_or_b32 v238, v237, 4, v238
	v_lshrrev_b32_e32 v237, 5, v235
	v_lshl_or_b32 v238, v237, 11, v238
	v_and_b32_e32 v237, 31, v235
	v_mul_u32_u24_e32 v237, 0x3800, v237
	v_add_u32_e32 v230, v237, v238
	v_add_u32_e32 v234, 1024, v83
	v_mul_u32_u24_e32 v235, 0x7c2, v234
	v_lshrrev_b32_e32 v235, 16, v235
	v_mul_u32_u24_e32 v236, 33, v235
	v_sub_u32_e32 v236, v234, v236
	v_and_b32_e32 v237, 15, v236
	v_lshrrev_b32_e32 v238, 1, v237
	v_lshlrev_b32_e32 v238, 6, v238
	v_and_b32_e32 v237, 1, v237
	v_lshl_or_b32 v238, v237, 5, v238
	v_lshrrev_b32_e32 v237, 4, v236
	v_lshl_or_b32 v238, v237, 4, v238
	v_lshrrev_b32_e32 v237, 5, v235
	v_lshl_or_b32 v238, v237, 11, v238
	v_and_b32_e32 v237, 31, v235
	v_mul_u32_u24_e32 v237, 0x3800, v237
	v_add_u32_e32 v231, v237, v238
	v_add_u32_e32 v234, 1536, v83
	v_mul_u32_u24_e32 v235, 0x7c2, v234
	v_lshrrev_b32_e32 v235, 16, v235
	v_mul_u32_u24_e32 v236, 33, v235
	v_sub_u32_e32 v236, v234, v236
	v_and_b32_e32 v237, 15, v236
	v_lshrrev_b32_e32 v238, 1, v237
	v_lshlrev_b32_e32 v238, 6, v238
	v_and_b32_e32 v237, 1, v237
	v_lshl_or_b32 v238, v237, 5, v238
	v_lshrrev_b32_e32 v237, 4, v236
	v_lshl_or_b32 v238, v237, 4, v238
	v_lshrrev_b32_e32 v237, 5, v235
	v_lshl_or_b32 v238, v237, 11, v238
	v_and_b32_e32 v237, 31, v235
	v_mul_u32_u24_e32 v237, 0x3800, v237
	v_add_u32_e32 v232, v237, v238
	v_add_u32_e32 v234, 2048, v83
	v_mul_u32_u24_e32 v235, 0x7c2, v234
	v_lshrrev_b32_e32 v235, 16, v235
	v_mul_u32_u24_e32 v236, 33, v235
	v_sub_u32_e32 v236, v234, v236
	v_and_b32_e32 v237, 15, v236
	v_lshrrev_b32_e32 v238, 1, v237
	v_lshlrev_b32_e32 v238, 6, v238
	v_and_b32_e32 v237, 1, v237
	v_lshl_or_b32 v238, v237, 5, v238
	v_lshrrev_b32_e32 v237, 4, v236
	v_lshl_or_b32 v238, v237, 4, v238
	v_lshrrev_b32_e32 v237, 5, v235
	v_lshl_or_b32 v238, v237, 11, v238
	v_and_b32_e32 v237, 31, v235
	v_mul_u32_u24_e32 v237, 0x3800, v237
	v_add_u32_e32 v233, v237, v238
	s_add_u32 s98, s100, s70
	s_addc_u32 s99, s101, s71
	s_lshl_b32 m0, s55, 10
	s_nop 0
	global_load_lds_dwordx4 v229, s[98:99]
	s_add_u32 m0, m0, 0x2000
	s_nop 0
	global_load_lds_dwordx4 v230, s[98:99]
	s_add_u32 m0, m0, 0x2000
	s_nop 0
	global_load_lds_dwordx4 v231, s[98:99]
	s_add_u32 m0, m0, 0x2000
	s_nop 0
	global_load_lds_dwordx4 v232, s[98:99]
	s_cmp_lg_u32 s55, 0
	s_cbranch_scc1 .Ldma_skip_pro
	s_mov_b32 m0, 0x8000
	s_nop 0
	global_load_lds_dwordx4 v233, s[98:99]

; #define LAS __attribute__((address_space(3)))
; __device__ __forceinline__ unsigned pk2(float lo, float hi) { unsigned r; asm("v_cvt_pk_bf16_f32 %0, %1, %2" : "=v"(r) : "v"(lo), "v"(hi)); return r; }
; #define MFMA16(a, b, c) __builtin_amdgcn_mfma_f32_16x16x32_bf16((a), (b), (c), 0, 0, 0)
; #define LDS_BARRIER() do { asm volatile("s_waitcnt lgkmcnt(0)" ::: "memory"); __builtin_amdgcn_s_barrier(); asm volatile("" ::: "memory"); } while (0)
; __device__ __forceinline__ void mlstm_item(const Args& a, LAS unsigned char* L, bool sample, int b, int hh, int sl, bool dry = false) {
;     ...
;         {
;             const int tt = wave & 1, vt = wave >> 1, t = tt * 16 + lr;
;             const bf16x8 Bs = *(const LAS bf16x8*)(L + L_SS + t * 80 + g * 16);
;             const f32x4 z4 = (f32x4){0.f, 0.f, 0.f, 0.f};
;             const bf16x8 Av = *(const LAS bf16x8*)(L + L_VT + (vt * 16 + lr) * 80 + g * 16);
;             bf16x8 Af[8], Bf[8];
; #pragma unroll
;             for (int kk = 0; kk < 8; ++kk) { Af[kk] = *(const LAS bf16x8*)(L + L_CS + (vt * 16 + lr) * 528 + kk * 64 + g * 16); Bf[kk] = *(const LAS bf16x8*)(L + L_QS + t * 528 + kk * 64 + g * 16); }
;             __builtin_amdgcn_sched_barrier(0);
;             f32x4 sM = MFMA16(Av, Bs, z4);
;             f32x4 cM = z4;
; #pragma unroll
;             for (int kk = 0; kk < 8; ++kk) cM = MFMA16(Af[kk], Bf[kk], cM);
;             const float d0 = __expf(m0c + GFM[c * 32 + t]), en = GEN[c * 32 + t];
;             const LAS float* NQ = (const LAS float*)(L + L_NQ);
;             const float nq = (NQ[t] + NQ[32 + t]) + d0 * (NQ[64 + t] + NQ[96 + t]);
;             const float inv = __builtin_amdgcn_rcpf(fmaxf(fabsf(nq), en));
;             float hv[4];
; #pragma unroll
;             for (int j = 0; j < 4; ++j) hv[j] = (sM[j] + d0 * cM[j]) * inv;
;             if (dry) *(u32x2*)((bf16_t*)a.out + (size_t)(rowbase + c * 32 + t) * 1024 + hh * 256 + sl * 64 + vt * 16 + g * 4) = (u32x2){pk2(hv[0], hv[1]), pk2(hv[2], hv[3])};
;             else *(u32x2*)(U + (size_t)(rowbase + c * 32 + t) * LDU + C_V + hh * 256 + sl * 64 + vt * 16 + g * 4) = (u32x2){pk2(hv[0], hv[1]), pk2(hv[2], hv[3])};
;         }
;         LDS_BARRIER();
;         WRITE_CS();
.Ldma_skip_loop:
	s_waitcnt lgkmcnt(0)
	v_mfma_f32_16x16x32_bf16 v[40:43], v[56:59], v[136:139], v[40:43]
	v_add_u32_e32 v58, v70, v99
	v_add_u32_e32 v57, v104, v222
	v_mfma_f32_16x16x32_bf16 v[32:35], v[116:119], v[120:123], v[32:35]
	v_mfma_f32_16x16x32_bf16 v[28:31], v[116:119], v[124:127], v[28:31]
	v_mfma_f32_16x16x32_bf16 v[24:27], v[116:119], v[128:131], v[24:27]
	v_mfma_f32_16x16x32_bf16 v[20:23], v[116:119], v[132:135], v[20:23]
	v_mfma_f32_16x16x32_bf16 v[16:19], v[116:119], v[136:139], v[16:19]
	ds_read_b128 v[116:119], v91 offset:46592
	ds_read_b128 v[120:123], v58 offset:33792
	ds_read_b128 v[124:127], v90 offset:49152
	ds_read_b128 v[132:135], v90 offset:49184
	ds_read_b128 v[140:143], v90 offset:49216
	ds_read_b128 v[148:151], v90 offset:49248
	ds_read_b128 v[156:159], v90 offset:49280
	ds_read_b128 v[164:167], v90 offset:49312
	ds_read_b128 v[172:175], v90 offset:49344
	ds_read_b128 v[182:185], v90 offset:49376
	v_add_u32_e32 v56, 0, v110
	v_add_u32_e32 v59, 0x16500, v56
	ds_read_b32 v59, v59
	v_add_u32_e32 v56, 0x1a500, v56
	ds_read2_b32 v[128:129], v89 offset1:32
	ds_read_b32 v56, v56
	ds_read2_b32 v[130:131], v89 offset0:64 offset1:96
	v_cvt_pk_bf16_f32 v240, v36, v37
	v_cvt_pk_bf16_f32 v241, v38, v39
	v_cvt_pk_bf16_f32 v242, v32, v33
	v_cvt_pk_bf16_f32 v243, v34, v35
	v_cvt_pk_bf16_f32 v244, v52, v53
	v_cvt_pk_bf16_f32 v245, v54, v55
	v_cvt_pk_bf16_f32 v246, v28, v29
	v_cvt_pk_bf16_f32 v247, v30, v31
	s_waitcnt lgkmcnt(0)
	s_barrier
	ds_write2_b64 v248, v[240:241], v[242:243] offset1:2
	ds_write2_b64 v249, v[244:245], v[246:247] offset0:32 offset1:34
	v_cvt_pk_bf16_f32 v240, v48, v49
	v_cvt_pk_bf16_f32 v241, v50, v51
	v_cvt_pk_bf16_f32 v242, v24, v25
	v_cvt_pk_bf16_f32 v243, v26, v27
	ds_write2_b64 v85, v[240:241], v[242:243] offset1:2
	v_cvt_pk_bf16_f32 v244, v44, v45
	v_cvt_pk_bf16_f32 v245, v46, v47
	v_cvt_pk_bf16_f32 v246, v20, v21
	v_cvt_pk_bf16_f32 v247, v22, v23
	ds_write2_b64 v250, v[244:245], v[246:247] offset0:32 offset1:34
	v_cvt_pk_bf16_f32 v240, v40, v41
	v_cvt_pk_bf16_f32 v241, v42, v43
	v_cvt_pk_bf16_f32 v242, v16, v17
	v_cvt_pk_bf16_f32 v243, v18, v19
	ds_write2_b64 v67, v[240:241], v[242:243] offset0:32 offset1:34
	v_mfma_f32_16x16x32_bf16 v[124:127], v[124:127], v[190:193], 0
	v_mfma_f32_16x16x32_bf16 v[124:127], v[132:135], v[194:197], v[124:127]
	v_mfma_f32_16x16x32_bf16 v[124:127], v[140:143], v[198:201], v[124:127]
	v_add_f32_e32 v59, v115, v59
	v_mul_f32_e32 v59, 0x3fb8aa3b, v59
	v_exp_f32_e32 v59, v59
	v_mfma_f32_16x16x32_bf16 v[124:127], v[148:151], v[202:205], v[124:127]
	v_mov_b32_e32 v132, v128
	v_mov_b32_e32 v133, v130
	v_mov_b32_e32 v130, v129
	v_mfma_f32_16x16x32_bf16 v[124:127], v[156:159], v[206:209], v[124:127]
	v_add_f32_e64 v128, v132, v130
	v_add_f32_e64 v129, v133, v131
	v_max_f32_e32 v56, v56, v56
	v_fmac_f32_e32 v128, v59, v129
	v_mfma_f32_16x16x32_bf16 v[124:127], v[164:167], v[210:213], v[124:127]
	v_max_f32_e64 v56, |v128|, v56
	v_rcp_f32_e32 v56, v56
	s_lshl_b32 s42, s53, 1
	v_mfma_f32_16x16x32_bf16 v[124:127], v[172:175], v[214:217], v[124:127]
	s_mov_b32 s59, s43
	s_add_i32 s16, s16, 4
	s_add_u32 s70, s70, 0x70000
	v_mfma_f32_16x16x32_bf16 v[124:127], v[182:185], v[218:221], v[124:127]
	s_addc_u32 s71, s71, 0
	v_add_u32_e32 v114, 0x80, v114
	v_add_u32_e32 v110, 0x80, v110
	v_mfma_f32_16x16x32_bf16 v[116:119], v[120:123], v[116:119], 0
	v_add_u32_e32 v111, 0x80, v111
	s_nop 7
	s_nop 1
	v_fma_f32 v76, v124, v59, v116
	v_fma_f32 v115, v125, v59, v117
	v_fma_f32 v116, v126, v59, v118
	v_fmac_f32_e32 v119, v127, v59
	v_mul_f32_e32 v76, v76, v56
	v_mul_f32_e32 v115, v115, v56
	v_mul_f32_e32 v117, v116, v56
	v_mul_f32_e32 v56, v119, v56
	v_mov_b64_e32 v[118:119], s[28:29]
	v_mad_i64_i32 v[118:119], s[72:73], v109, s84, v[118:119]
	v_lshl_add_u64 v[118:119], v[118:119], 0, s[42:43]
	v_lshl_add_u64 v[118:119], v[118:119], 0, s[58:59]
	v_lshl_add_u64 v[118:119], s[56:57], 1, v[118:119]
	v_lshl_add_u64 v[118:119], v[118:119], 0, v[60:61]
	v_add_co_u32_e32 v118, vcc, s85, v118
	v_cvt_pk_bf16_f32 v116, v76, v115
	v_cvt_pk_bf16_f32 v117, v117, v56
	v_add_u32_e32 v59, 0xc000, v113
	s_nop 0
	v_addc_co_u32_e32 v119, vcc, 0, v119, vcc
	global_store_dwordx2 v[118:119], v[116:117], off
	v_add_u32_e32 v76, 0xe000, v113
	v_add_u32_e32 v115, 0xe000, v86
	v_add_u32_e32 v109, 32, v109
	s_cmp_eq_u32 s70, 0x1b90000
	s_cbranch_scc1 .LBB0_676
